# K-loop back-edge rotation (7.11): loop-back barrier is the loop head, branch before it, exit barrier copy; body byte phase pinned
# speedup vs baseline: 1.0037x; 1.0037x over previous
.LBB0_743:
	s_add_u32 s6, s6, 0x80
	s_addc_u32 s7, s7, 0
	s_add_u32 s42, s4, 0x100
	s_addc_u32 s43, s5, 0
	s_mov_b32 s4, 0
	s_nop 0
	s_nop 0
	s_nop 0
	s_nop 0
	s_nop 0
	s_nop 0
	s_nop 0
	s_nop 0
	s_nop 0
	s_nop 0
	s_nop 0
	s_nop 0
	s_nop 0
	s_nop 0
	s_branch .Lk_body

.Lk_body:
	s_add_i32 s44, s4, 2
	s_add_u32 s8, s6, 0x80
	s_addc_u32 s5, s7, 0
	s_add_i32 s45, 0, 0x10000
	v_add_u32_e32 v140, s45, v234
	ds_read_b128 v[128:131], v140
	ds_read_b128 v[132:135], v140 offset:1024
	ds_read_b128 v[136:139], v140 offset:2048
	ds_read_b128 v[140:143], v140 offset:3072
	s_cmp_eq_u32 s27, s4
	s_cselect_b32 s4, s90, s8
	s_cselect_b32 s5, s91, s5
	s_cselect_b32 s9, s93, s43
	s_cselect_b32 s8, s92, s42
	v_lshl_add_u64 v[214:215], s[6:7], 0, v[206:207]
	s_add_i32 m0, s74, 0xc000
	ds_read_b128 v[144:147], v235
	ds_read_b128 v[148:151], v235 offset:1024
	ds_read_b128 v[152:155], v235 offset:2048
	ds_read_b128 v[156:159], v235 offset:3072
	ds_read_b128 v[160:163], v235 offset:4096
	ds_read_b128 v[164:167], v235 offset:5120
	ds_read_b128 v[168:171], v235 offset:6144
	ds_read_b128 v[210:213], v235 offset:7168
	global_load_lds_dwordx4 v[214:215], off
	v_lshl_add_u64 v[214:215], s[6:7], 0, v[208:209]
	s_add_i32 m0, s74, 0xe000
	s_nop 0
	global_load_lds_dwordx4 v[214:215], off
	s_waitcnt lgkmcnt(8)
	s_barrier
	s_waitcnt lgkmcnt(0)
	s_waitcnt lgkmcnt(0)
	v_mfma_f32_16x16x32_bf16 v[108:111], v[128:131], v[144:147], v[108:111]
	v_mfma_f32_16x16x32_bf16 v[104:107], v[136:139], v[144:147], v[104:107]
	v_mfma_f32_16x16x32_bf16 v[92:95], v[128:131], v[152:155], v[92:95]
	v_mfma_f32_16x16x32_bf16 v[80:83], v[136:139], v[152:155], v[80:83]
	v_mfma_f32_16x16x32_bf16 v[68:71], v[128:131], v[160:163], v[68:71]
	v_mfma_f32_16x16x32_bf16 v[56:59], v[136:139], v[160:163], v[56:59]
	v_mfma_f32_16x16x32_bf16 v[44:47], v[128:131], v[168:171], v[44:47]
	v_mfma_f32_16x16x32_bf16 v[32:35], v[136:139], v[168:171], v[32:35]
	v_mfma_f32_16x16x32_bf16 v[108:111], v[132:135], v[148:151], v[108:111]
	v_mfma_f32_16x16x32_bf16 v[104:107], v[140:143], v[148:151], v[104:107]
	v_mfma_f32_16x16x32_bf16 v[92:95], v[132:135], v[156:159], v[92:95]
	v_mfma_f32_16x16x32_bf16 v[80:83], v[140:143], v[156:159], v[80:83]
	v_mfma_f32_16x16x32_bf16 v[68:71], v[132:135], v[164:167], v[68:71]
	v_mfma_f32_16x16x32_bf16 v[56:59], v[140:143], v[164:167], v[56:59]
	v_mfma_f32_16x16x32_bf16 v[44:47], v[132:135], v[210:213], v[44:47]
	v_mfma_f32_16x16x32_bf16 v[32:35], v[140:143], v[210:213], v[32:35]
	s_barrier
	s_add_i32 s45, s45, s97
	v_add_u32_e32 v172, s3, v234
	v_lshl_add_u64 v[244:245], s[8:9], 0, v[184:185]
	s_mov_b32 m0, s45
	ds_read_b128 v[214:217], v172
	ds_read_b128 v[218:221], v172 offset:1024
	ds_read_b128 v[236:239], v172 offset:2048
	ds_read_b128 v[240:243], v172 offset:3072
	global_load_lds_dwordx4 v[244:245], off
	v_lshl_add_u64 v[246:247], s[8:9], 0, v[188:189]
	s_add_i32 m0, s45, 0x2000
	s_nop 0
	global_load_lds_dwordx4 v[246:247], off
	s_barrier
	s_waitcnt lgkmcnt(0)
	s_waitcnt lgkmcnt(0)
	v_mfma_f32_16x16x32_bf16 v[124:127], v[214:217], v[144:147], v[124:127]
	v_mfma_f32_16x16x32_bf16 v[120:123], v[236:239], v[144:147], v[120:123]
	v_mfma_f32_16x16x32_bf16 v[116:119], v[214:217], v[152:155], v[116:119]
	v_mfma_f32_16x16x32_bf16 v[112:115], v[236:239], v[152:155], v[112:115]
	v_mfma_f32_16x16x32_bf16 v[100:103], v[214:217], v[160:163], v[100:103]
	v_mfma_f32_16x16x32_bf16 v[96:99], v[236:239], v[160:163], v[96:99]
	v_mfma_f32_16x16x32_bf16 v[76:79], v[214:217], v[168:171], v[76:79]
	v_mfma_f32_16x16x32_bf16 v[72:75], v[236:239], v[168:171], v[72:75]
	v_mfma_f32_16x16x32_bf16 v[124:127], v[218:221], v[148:151], v[124:127]
	v_mfma_f32_16x16x32_bf16 v[120:123], v[240:243], v[148:151], v[120:123]
	v_mfma_f32_16x16x32_bf16 v[116:119], v[218:221], v[156:159], v[116:119]
	v_mfma_f32_16x16x32_bf16 v[112:115], v[240:243], v[156:159], v[112:115]
	v_mfma_f32_16x16x32_bf16 v[100:103], v[218:221], v[164:167], v[100:103]
	v_mfma_f32_16x16x32_bf16 v[96:99], v[240:243], v[164:167], v[96:99]
	v_mfma_f32_16x16x32_bf16 v[76:79], v[218:221], v[210:213], v[76:79]
	v_mfma_f32_16x16x32_bf16 v[72:75], v[240:243], v[210:213], v[72:75]
	s_mov_b32 m0, s74
	v_lshl_add_u64 v[248:249], s[4:5], 0, v[182:183]
	s_barrier
	ds_read_b128 v[144:147], v235 offset:16384
	ds_read_b128 v[148:151], v235 offset:17408
	ds_read_b128 v[152:155], v235 offset:18432
	ds_read_b128 v[156:159], v235 offset:19456
	ds_read_b128 v[160:163], v235 offset:20480
	ds_read_b128 v[164:167], v235 offset:21504
	ds_read_b128 v[168:171], v235 offset:22528
	ds_read_b128 v[210:213], v235 offset:23552
	global_load_lds_dwordx4 v[248:249], off
	v_lshl_add_u64 v[250:251], s[4:5], 0, v[186:187]
	s_mov_b32 m0, s56
	s_nop 0
	global_load_lds_dwordx4 v[250:251], off
	s_barrier
	s_waitcnt lgkmcnt(0)
	s_waitcnt lgkmcnt(0)
	v_mfma_f32_16x16x32_bf16 v[52:55], v[128:131], v[144:147], v[52:55]
	v_mfma_f32_16x16x32_bf16 v[48:51], v[136:139], v[144:147], v[48:51]
	v_mfma_f32_16x16x32_bf16 v[28:31], v[128:131], v[152:155], v[28:31]
	v_mfma_f32_16x16x32_bf16 v[24:27], v[136:139], v[152:155], v[24:27]
	v_mfma_f32_16x16x32_bf16 v[12:15], v[128:131], v[160:163], v[12:15]
	v_mfma_f32_16x16x32_bf16 v[8:11], v[136:139], v[160:163], v[8:11]
	v_mfma_f32_16x16x32_bf16 v[4:7], v[128:131], v[168:171], v[4:7]
	v_mfma_f32_16x16x32_bf16 v[0:3], v[136:139], v[168:171], v[0:3]
	v_mfma_f32_16x16x32_bf16 v[52:55], v[132:135], v[148:151], v[52:55]
	v_mfma_f32_16x16x32_bf16 v[48:51], v[140:143], v[148:151], v[48:51]
	v_mfma_f32_16x16x32_bf16 v[28:31], v[132:135], v[156:159], v[28:31]
	v_mfma_f32_16x16x32_bf16 v[24:27], v[140:143], v[156:159], v[24:27]
	v_mfma_f32_16x16x32_bf16 v[12:15], v[132:135], v[164:167], v[12:15]
	v_mfma_f32_16x16x32_bf16 v[8:11], v[140:143], v[164:167], v[8:11]
	v_mfma_f32_16x16x32_bf16 v[4:7], v[132:135], v[210:213], v[4:7]
	v_mfma_f32_16x16x32_bf16 v[0:3], v[140:143], v[210:213], v[0:3]
	s_barrier
	s_add_u32 s8, s8, s78
	s_addc_u32 s9, s9, 0
	s_add_i32 s45, s3, s97
	v_lshl_add_u64 v[252:253], s[8:9], 0, v[184:185]
	s_mov_b32 m0, s45
	v_lshl_add_u64 v[230:231], s[8:9], 0, v[188:189]
	global_load_lds_dwordx4 v[252:253], off
	s_add_i32 m0, s45, 0x2000
	s_nop 0
	global_load_lds_dwordx4 v[230:231], off
	s_waitcnt vmcnt(6)
	s_barrier
	v_mfma_f32_16x16x32_bf16 v[88:91], v[214:217], v[144:147], v[88:91]
	v_mfma_f32_16x16x32_bf16 v[84:87], v[236:239], v[144:147], v[84:87]
	v_mfma_f32_16x16x32_bf16 v[64:67], v[214:217], v[152:155], v[64:67]
	v_mfma_f32_16x16x32_bf16 v[60:63], v[236:239], v[152:155], v[60:63]
	v_mfma_f32_16x16x32_bf16 v[40:43], v[214:217], v[160:163], v[40:43]
	v_mfma_f32_16x16x32_bf16 v[36:39], v[236:239], v[160:163], v[36:39]
	v_mfma_f32_16x16x32_bf16 v[20:23], v[214:217], v[168:171], v[20:23]
	v_mfma_f32_16x16x32_bf16 v[16:19], v[236:239], v[168:171], v[16:19]
	v_mfma_f32_16x16x32_bf16 v[88:91], v[218:221], v[148:151], v[88:91]
	v_mfma_f32_16x16x32_bf16 v[84:87], v[240:243], v[148:151], v[84:87]
	v_mfma_f32_16x16x32_bf16 v[64:67], v[218:221], v[156:159], v[64:67]
	v_mfma_f32_16x16x32_bf16 v[60:63], v[240:243], v[156:159], v[60:63]
	v_mfma_f32_16x16x32_bf16 v[40:43], v[218:221], v[164:167], v[40:43]
	v_mfma_f32_16x16x32_bf16 v[36:39], v[240:243], v[164:167], v[36:39]
	v_mfma_f32_16x16x32_bf16 v[20:23], v[218:221], v[210:213], v[20:23]
	v_mfma_f32_16x16x32_bf16 v[16:19], v[240:243], v[210:213], v[16:19]
	s_add_i32 s8, 0, 0x18000
	v_add_u32_e32 v140, s8, v234
	s_barrier
	ds_read_b128 v[128:131], v140
	ds_read_b128 v[132:135], v140 offset:1024
	ds_read_b128 v[136:139], v140 offset:2048
	ds_read_b128 v[140:143], v140 offset:3072
	s_add_u32 s4, s4, s60
	s_addc_u32 s5, s5, 0
	s_mov_b32 m0, s57
	v_lshl_add_u64 v[214:215], s[4:5], 0, v[182:183]
	ds_read_b128 v[144:147], v235 offset:32768
	ds_read_b128 v[148:151], v235 offset:33792
	ds_read_b128 v[152:155], v235 offset:34816
	ds_read_b128 v[156:159], v235 offset:35840
	ds_read_b128 v[160:163], v235 offset:36864
	ds_read_b128 v[164:167], v235 offset:37888
	ds_read_b128 v[168:171], v235 offset:38912
	ds_read_b128 v[210:213], v235 offset:39936
	global_load_lds_dwordx4 v[214:215], off
	v_lshl_add_u64 v[214:215], s[4:5], 0, v[186:187]
	s_mov_b32 m0, s68
	s_nop 0
	global_load_lds_dwordx4 v[214:215], off
	s_waitcnt lgkmcnt(8)
	s_barrier
	s_waitcnt lgkmcnt(0)
	s_waitcnt lgkmcnt(0)
	v_mfma_f32_16x16x32_bf16 v[108:111], v[128:131], v[144:147], v[108:111]
	v_mfma_f32_16x16x32_bf16 v[104:107], v[136:139], v[144:147], v[104:107]
	v_mfma_f32_16x16x32_bf16 v[92:95], v[128:131], v[152:155], v[92:95]
	v_mfma_f32_16x16x32_bf16 v[80:83], v[136:139], v[152:155], v[80:83]
	v_mfma_f32_16x16x32_bf16 v[68:71], v[128:131], v[160:163], v[68:71]
	v_mfma_f32_16x16x32_bf16 v[56:59], v[136:139], v[160:163], v[56:59]
	v_mfma_f32_16x16x32_bf16 v[44:47], v[128:131], v[168:171], v[44:47]
	v_mfma_f32_16x16x32_bf16 v[32:35], v[136:139], v[168:171], v[32:35]
	v_mfma_f32_16x16x32_bf16 v[108:111], v[132:135], v[148:151], v[108:111]
	v_mfma_f32_16x16x32_bf16 v[104:107], v[140:143], v[148:151], v[104:107]
	v_mfma_f32_16x16x32_bf16 v[92:95], v[132:135], v[156:159], v[92:95]
	v_mfma_f32_16x16x32_bf16 v[80:83], v[140:143], v[156:159], v[80:83]
	v_mfma_f32_16x16x32_bf16 v[68:71], v[132:135], v[164:167], v[68:71]
	v_mfma_f32_16x16x32_bf16 v[56:59], v[140:143], v[164:167], v[56:59]
	v_mfma_f32_16x16x32_bf16 v[44:47], v[132:135], v[210:213], v[44:47]
	v_mfma_f32_16x16x32_bf16 v[32:35], v[140:143], v[210:213], v[32:35]
	s_barrier
	s_add_i32 s4, 0, 0x1c000
	s_add_i32 s5, s8, s97
	v_add_u32_e32 v172, s4, v234
	v_lshl_add_u64 v[244:245], v[244:245], 0, s[54:55]
	s_mov_b32 m0, s5
	ds_read_b128 v[214:217], v172
	ds_read_b128 v[218:221], v172 offset:1024
	ds_read_b128 v[236:239], v172 offset:2048
	ds_read_b128 v[240:243], v172 offset:3072
	global_load_lds_dwordx4 v[244:245], off
	v_lshl_add_u64 v[244:245], v[246:247], 0, s[54:55]
	s_add_i32 m0, s5, 0x2000
	s_nop 0
	global_load_lds_dwordx4 v[244:245], off
	s_barrier
	s_waitcnt lgkmcnt(0)
	s_waitcnt lgkmcnt(0)
	v_mfma_f32_16x16x32_bf16 v[124:127], v[214:217], v[144:147], v[124:127]
	v_mfma_f32_16x16x32_bf16 v[120:123], v[236:239], v[144:147], v[120:123]
	v_mfma_f32_16x16x32_bf16 v[116:119], v[214:217], v[152:155], v[116:119]
	v_mfma_f32_16x16x32_bf16 v[112:115], v[236:239], v[152:155], v[112:115]
	v_mfma_f32_16x16x32_bf16 v[100:103], v[214:217], v[160:163], v[100:103]
	v_mfma_f32_16x16x32_bf16 v[96:99], v[236:239], v[160:163], v[96:99]
	v_mfma_f32_16x16x32_bf16 v[76:79], v[214:217], v[168:171], v[76:79]
	v_mfma_f32_16x16x32_bf16 v[72:75], v[236:239], v[168:171], v[72:75]
	v_mfma_f32_16x16x32_bf16 v[124:127], v[218:221], v[148:151], v[124:127]
	v_mfma_f32_16x16x32_bf16 v[120:123], v[240:243], v[148:151], v[120:123]
	v_mfma_f32_16x16x32_bf16 v[116:119], v[218:221], v[156:159], v[116:119]
	v_mfma_f32_16x16x32_bf16 v[112:115], v[240:243], v[156:159], v[112:115]
	v_mfma_f32_16x16x32_bf16 v[100:103], v[218:221], v[164:167], v[100:103]
	v_mfma_f32_16x16x32_bf16 v[96:99], v[240:243], v[164:167], v[96:99]
	v_mfma_f32_16x16x32_bf16 v[76:79], v[218:221], v[210:213], v[76:79]
	v_mfma_f32_16x16x32_bf16 v[72:75], v[240:243], v[210:213], v[72:75]
	s_mov_b32 m0, s69
	v_lshl_add_u64 v[244:245], v[248:249], 0, s[54:55]
	s_barrier
	ds_read_b128 v[144:147], v235 offset:49152
	ds_read_b128 v[148:151], v235 offset:50176
	ds_read_b128 v[152:155], v235 offset:51200
	ds_read_b128 v[156:159], v235 offset:52224
	ds_read_b128 v[160:163], v235 offset:53248
	ds_read_b128 v[164:167], v235 offset:54272
	ds_read_b128 v[168:171], v235 offset:55296
	ds_read_b128 v[210:213], v235 offset:56320
	global_load_lds_dwordx4 v[244:245], off
	v_lshl_add_u64 v[244:245], v[250:251], 0, s[54:55]
	s_mov_b32 m0, s26
	s_nop 0
	global_load_lds_dwordx4 v[244:245], off
	s_barrier
	s_waitcnt lgkmcnt(0)
	s_waitcnt lgkmcnt(0)
	v_mfma_f32_16x16x32_bf16 v[52:55], v[128:131], v[144:147], v[52:55]
	v_mfma_f32_16x16x32_bf16 v[48:51], v[136:139], v[144:147], v[48:51]
	v_mfma_f32_16x16x32_bf16 v[28:31], v[128:131], v[152:155], v[28:31]
	v_mfma_f32_16x16x32_bf16 v[24:27], v[136:139], v[152:155], v[24:27]
	v_mfma_f32_16x16x32_bf16 v[12:15], v[128:131], v[160:163], v[12:15]
	v_mfma_f32_16x16x32_bf16 v[8:11], v[136:139], v[160:163], v[8:11]
	v_mfma_f32_16x16x32_bf16 v[4:7], v[128:131], v[168:171], v[4:7]
	v_mfma_f32_16x16x32_bf16 v[0:3], v[136:139], v[168:171], v[0:3]
	v_mfma_f32_16x16x32_bf16 v[52:55], v[132:135], v[148:151], v[52:55]
	v_mfma_f32_16x16x32_bf16 v[48:51], v[140:143], v[148:151], v[48:51]
	v_mfma_f32_16x16x32_bf16 v[28:31], v[132:135], v[156:159], v[28:31]
	v_mfma_f32_16x16x32_bf16 v[24:27], v[140:143], v[156:159], v[24:27]
	v_mfma_f32_16x16x32_bf16 v[12:15], v[132:135], v[164:167], v[12:15]
	v_mfma_f32_16x16x32_bf16 v[8:11], v[140:143], v[164:167], v[8:11]
	v_mfma_f32_16x16x32_bf16 v[4:7], v[132:135], v[210:213], v[4:7]
	v_mfma_f32_16x16x32_bf16 v[0:3], v[140:143], v[210:213], v[0:3]
	s_barrier
	s_add_i32 s4, s4, s97
	v_lshl_add_u64 v[128:129], v[252:253], 0, s[54:55]
	s_mov_b32 m0, s4
	s_nop 0
	global_load_lds_dwordx4 v[128:129], off
	v_lshl_add_u64 v[128:129], v[230:231], 0, s[54:55]
	s_add_i32 m0, s4, 0x2000
	s_nop 0
	global_load_lds_dwordx4 v[128:129], off
	s_waitcnt vmcnt(6)
	s_barrier
	v_mfma_f32_16x16x32_bf16 v[88:91], v[214:217], v[144:147], v[88:91]
	v_mfma_f32_16x16x32_bf16 v[84:87], v[236:239], v[144:147], v[84:87]
	v_mfma_f32_16x16x32_bf16 v[64:67], v[214:217], v[152:155], v[64:67]
	v_mfma_f32_16x16x32_bf16 v[60:63], v[236:239], v[152:155], v[60:63]
	v_mfma_f32_16x16x32_bf16 v[40:43], v[214:217], v[160:163], v[40:43]
	v_mfma_f32_16x16x32_bf16 v[36:39], v[236:239], v[160:163], v[36:39]
	v_mfma_f32_16x16x32_bf16 v[20:23], v[214:217], v[168:171], v[20:23]
	v_mfma_f32_16x16x32_bf16 v[16:19], v[236:239], v[168:171], v[16:19]
	v_mfma_f32_16x16x32_bf16 v[88:91], v[218:221], v[148:151], v[88:91]
	v_mfma_f32_16x16x32_bf16 v[84:87], v[240:243], v[148:151], v[84:87]
	v_mfma_f32_16x16x32_bf16 v[64:67], v[218:221], v[156:159], v[64:67]
	v_mfma_f32_16x16x32_bf16 v[60:63], v[240:243], v[156:159], v[60:63]
	v_mfma_f32_16x16x32_bf16 v[40:43], v[218:221], v[164:167], v[40:43]
	v_mfma_f32_16x16x32_bf16 v[36:39], v[240:243], v[164:167], v[36:39]
	v_mfma_f32_16x16x32_bf16 v[20:23], v[218:221], v[210:213], v[20:23]
	v_mfma_f32_16x16x32_bf16 v[16:19], v[240:243], v[210:213], v[16:19]
	s_add_u32 s6, s6, 0x100
	s_addc_u32 s7, s7, 0
	s_add_u32 s42, s42, 0x100
	s_addc_u32 s43, s43, 0
	s_cmp_ge_u32 s44, s73
	s_mov_b32 s4, s44
	s_cbranch_scc0 .LBB0_744
	s_barrier
	s_lshl_b32 s52, s30, 8
	s_cmp_lt_i32 s96, 2
	s_mov_b64 s[4:5], -1
	s_cbranch_scc1 .LBB0_898
	s_cmp_gt_i32 s96, 2
	s_cbranch_scc0 .LBB0_895
	s_add_i32 s30, s52, s82
	v_or_b32_e32 v210, s30, v179
	s_and_b32 s4, s10, -4
	s_cmp_lg_u32 s4, 4
	s_movk_i32 s4, 0x2000
	s_movk_i32 s6, 0x1fff
	v_or_b32_e32 v212, 16, v210
	v_cmp_gt_i32_e32 vcc, s4, v210
	v_cmp_lt_i32_e64 s[42:43], s6, v210
	s_mov_b64 s[4:5], -1
	v_ashrrev_i32_e32 v211, 31, v210
	s_movk_i32 s53, 0x1fff
	v_cmp_lt_i32_e64 s[46:47], s6, v212
	s_cbranch_scc0 .LBB0_829
	v_lshlrev_b32_e32 v128, 6, v212
	s_movk_i32 s4, 0x2000
	v_and_b32_e32 v128, 0x3f7c0, v128
	v_cmp_gt_i32_e64 s[44:45], s4, v212
	v_lshlrev_b32_e32 v219, 6, v210
	v_and_b32_e32 v144, 0x3f3c0, v219
	v_cndmask_b32_e64 v128, v225, v128, s[44:45]
	v_lshlrev_b32_e32 v172, 2, v128
	v_cndmask_b32_e32 v144, v225, v144, vcc
	v_lshl_add_u64 v[132:133], v[196:197], 0, v[172:173]
	v_lshl_add_u64 v[140:141], v[198:199], 0, v[172:173]
	v_lshlrev_b32_e32 v172, 2, v144
	v_lshl_add_u64 v[144:145], v[198:199], 0, v[172:173]
	global_load_dwordx4 v[128:131], v[132:133], off offset:16
	global_load_dwordx4 v[136:139], v[132:133], off
	s_nop 0
	global_load_dwordx4 v[132:135], v[140:141], off offset:16
	s_nop 0
	global_load_dwordx4 v[140:143], v[140:141], off
	s_nop 0
	global_load_dwordx4 v[156:159], v[144:145], off offset:16
	global_load_dwordx4 v[152:155], v[144:145], off
	v_lshl_add_u64 v[144:145], v[196:197], 0, v[172:173]
	global_load_dwordx4 v[160:163], v[144:145], off offset:16
	global_load_dwordx4 v[164:167], v[144:145], off
	s_cmp_gt_i32 s10, 3
	s_cselect_b64 s[4:5], -1, 0
	s_lshl_b32 s6, s10, 1
	s_add_i32 s7, s6, -16
	s_cmp_lt_i32 s10, 4
	s_cselect_b32 s6, s6, s7
	v_readlane_b32 s7, v255, 50
	s_or_b32 s6, s6, s7
	s_lshl_b32 s94, s6, 7
	s_ashr_i32 s95, s94, 31
	s_lshl_b64 s[6:7], s[94:95], 1
	v_lshl_add_u64 v[214:215], v[200:201], 0, s[6:7]
	s_waitcnt vmcnt(0)
	v_pk_mul_f32 v[144:145], v[126:127], v[154:155]
	v_pk_mul_f32 v[148:149], v[124:125], v[152:153]
	v_pk_fma_f32 v[146:147], v[110:111], v[166:167], v[144:145] neg_lo:[0,0,1] neg_hi:[0,0,1]
	v_pk_fma_f32 v[144:145], v[108:109], v[164:165], v[148:149] neg_lo:[0,0,1] neg_hi:[0,0,1]
	v_pk_mul_f32 v[148:149], v[122:123], v[158:159]
	v_pk_mul_f32 v[168:169], v[120:121], v[156:157]
	v_pk_fma_f32 v[150:151], v[106:107], v[162:163], v[148:149] neg_lo:[0,0,1] neg_hi:[0,0,1]
	v_pk_fma_f32 v[148:149], v[104:105], v[160:161], v[168:169] neg_lo:[0,0,1] neg_hi:[0,0,1]
	v_pk_mul_f32 v[166:167], v[126:127], v[166:167]
	v_pk_mul_f32 v[164:165], v[124:125], v[164:165]
	v_pk_mul_f32 v[162:163], v[122:123], v[162:163]
	v_pk_mul_f32 v[160:161], v[120:121], v[160:161]
	v_pk_fma_f32 v[154:155], v[110:111], v[154:155], v[166:167]
	v_pk_fma_f32 v[152:153], v[108:109], v[152:153], v[164:165]
	v_pk_fma_f32 v[158:159], v[106:107], v[158:159], v[162:163]
	v_pk_fma_f32 v[156:157], v[104:105], v[156:157], v[160:161]
	v_cvt_pk_bf16_f32 v160, v144, v145
	v_cvt_pk_bf16_f32 v161, v146, v147
	v_cvt_pk_bf16_f32 v162, v148, v149
	v_cvt_pk_bf16_f32 v163, v150, v151
	v_cvt_pk_bf16_f32 v164, v152, v153
	v_cvt_pk_bf16_f32 v165, v154, v155
	v_cvt_pk_bf16_f32 v166, v156, v157
	v_cvt_pk_bf16_f32 v167, v158, v159
	s_mov_b64 s[8:9], -1
	s_and_b64 vcc, exec, s[4:5]
	s_cbranch_vccz .LBB0_750
	s_movk_i32 s8, 0x1800
	v_mad_i64_i32 v[168:169], s[8:9], v210, s8, v[214:215]
	global_store_dwordx4 v[168:169], v[160:163], off
	global_store_dwordx4 v[168:169], v[164:167], off offset:128
	s_mov_b64 s[8:9], 0
